# GLA step: pool-branch GEMM runs before the sample queue on WGs>=128 (branch retarget only)
# speedup vs baseline: 1.0006x; 1.0006x over previous
.LBB0_408:
	s_waitcnt vmcnt(0)
	s_barrier
	s_branch .LBB0_339
.Lgla_end:
	s_barrier
